# extra work items (MLA ctx units, NA ctx units, third mixprep tile) moved off the blocks that own the seventh LRU chunk
# speedup vs baseline: 1.0098x; 1.0051x over previous
; template <int DQK, bool NA>
; __device__ __forceinline__ void attn_unit(LAS unsigned char* lds, const bf16_t* __restrict__ Qb, const bf16_t* __restrict__ Kb, const bf16_t* __restrict__ Vtb,
;                                           bf16_t* __restrict__ Yb  , int qb, const LAS float* rpbh, int tid) {
;     ...
;     const int wave = tid >> 6, lane = tid & 63, r = lane & 31, h = lane >> 5;
;     int n_tiles, rlo = 0;
;     if (qb == 0) n_tiles = 4;
;     else if (!NA) n_tiles = P / 64;
;     else { const int R = 4 * (qb - 1); rlo = clampi(R - 4, 0, 120); const int rhi = clampi(R - 1, 0, 120) + 7; n_tiles = 4 + rhi - rlo + 1; }
;     const int wrow = 4 * (qb - 1) + (wave >> 1);
;     const int r0w = clampi(wrow - 4, 0, 120);
;     const int qc = 32 * (wave & 1) + r, wst = clampi(qc - 8, 0, 48);
;     const int pq = 256 * qb + 32 * wave + r;
;     bf16x8 qf[NKS];
; #pragma unroll
;     for (int ks = 0; ks < NKS; ++ks) qf[ks] = *(const bf16x8*)(Qb + (size_t)pq * DQK + 16 * ks + 8 * h);
;     f32x16 O0, O1, O2;
; #pragma unroll
;     for (int v = 0; v < 16; ++v) { O0[v] = 0.f; O1[v] = 0.f; O2[v] = 0.f; }
;     float mrun = -1e30f;
;     const int krow = (r & ~12) | ((r & 4) << 1) | ((r & 8) >> 1);
; __global__ void __launch_bounds__(NTHR) fwd_megakernel(Args a_unused) {
;     ...
;                     for (int u = vb; u < 24; u += G) {
;                         const int b = u / 6, hh = u % 6; const size_t bh = (size_t)(b * 6 + hh);
;                         bf16_t* Yb = Y + (size_t)(MLAT + b * C) * D + 384 + hh * 64;
;                         attn_unit<96, false>(lds, (const bf16_t*)(ws + OFF_QM) + bh * P * 96, (const bf16_t*)(ws + OFF_KM) + bh * P * 96, (const bf16_t*)(ws + OFF_VMT) + bh * 64 * P, Yb, 0, nullptr, tid); }
.LBB0_215:
	s_mov_b32 s21, s93
	s_cmpk_lg_i32 s90, 0x100
	s_cbranch_scc1 .Lctx_noremap
	s_addk_i32 s21, 0xffd8
	s_cmp_lt_i32 s21, 0
	s_cbranch_scc1 .LBB0_245
.Lctx_noremap:
	s_cmp_gt_i32 s21, 23
	s_cbranch_scc1 .LBB0_245
	v_ashrrev_i32_e32 v2, 1, v230
	s_movk_i32 s0, 0xffe0
	v_bfe_u32 v10, v229, 5, 1
	v_bfi_b32 v2, s0, v2, v229
	v_mov_b64_e32 v[4:5], s[10:11]
	s_movk_i32 s0, 0xc0
	v_mad_i64_i32 v[6:7], s[0:1], v2, s0, v[4:5]
	v_lshlrev_b32_e32 v8, 4, v10
	v_mov_b32_e32 v9, v0
	v_lshl_add_u64 v[6:7], v[6:7], 0, v[8:9]
	s_mov_b64 s[0:1], 0x17370000
	s_waitcnt vmcnt(0)
	v_lshl_add_u64 v[154:155], v[6:7], 0, s[0:1]
	v_lshlrev_b32_e32 v7, 1, v229
	v_lshrrev_b32_e32 v9, 1, v229
	v_and_b32_e32 v6, 19, v229
	v_and_b32_e32 v7, 8, v7
	v_and_b32_e32 v9, 4, v9
	s_movk_i32 s0, 0x100
	v_or3_b32 v7, v7, v6, v9
	v_cmp_gt_i32_e64 s[38:39], s0, v230
	s_movk_i32 s0, 0xff
	v_ashrrev_i32_e32 v6, 3, v230
	v_cmp_lt_i32_e64 s[40:41], s0, v230
	v_mad_i64_i32 v[4:5], s[0:1], v6, s82, v[4:5]
	s_mov_b32 s0, 0x2aaaaaab
	v_add_u32_e32 v12, 0x200, v230
	v_mul_hi_i32 v13, v12, s0
	v_lshrrev_b32_e32 v14, 31, v13
	v_ashrrev_i32_e32 v13, 1, v13
	v_mul_hi_i32 v9, v230, s0
	s_movk_i32 s1, 0xd0
	v_add_u32_e32 v13, v13, v14
	v_lshrrev_b32_e32 v11, 31, v9
	v_ashrrev_i32_e32 v9, 1, v9
	v_mul_lo_u32 v14, v13, s1
	v_mul_lo_u32 v13, v13, 12
	v_add_u32_e32 v9, v9, v11
	v_sub_u32_e32 v12, v12, v13
	v_mul_lo_u32 v6, v6, s19
	v_mul_lo_u32 v11, v9, s1
	v_mul_lo_u32 v9, v9, 12
	v_lshlrev_b32_e32 v169, 4, v12
	v_add_u32_e32 v12, 0, v6
	v_lshlrev_b32_e32 v6, 4, v229
	v_and_b32_e32 v1, 31, v229
	v_ashrrev_i32_e32 v3, 31, v2
	v_lshlrev_b32_e32 v156, 3, v230
	v_sub_u32_e32 v9, v230, v9
	v_and_b32_e32 v6, 0x70, v6
	v_mad_u32_u24 v13, v7, s1, 0
	v_mov_b32_e32 v7, v0
	s_add_u32 s14, s10, 0x19890000
	v_add_u32_e32 v158, 0x1000, v156
	v_add_u32_e32 v11, 0, v11
	v_lshlrev_b32_e32 v9, 4, v9
	v_mad_u32_u24 v1, v1, s19, 0
	v_lshlrev_b64 v[160:161], 11, v[2:3]
	v_lshlrev_b32_e32 v2, 2, v10
	v_lshl_add_u64 v[4:5], v[4:5], 0, v[6:7]
	s_mov_b64 s[0:1], 0x1bdb0000
	s_addc_u32 s15, s11, 0
	v_ashrrev_i32_e32 v157, 31, v156
	v_ashrrev_i32_e32 v159, 31, v158
	v_add_u32_e32 v167, 0, v14
	v_lshl_add_u64 v[162:163], v[4:5], 0, s[0:1]
	s_lshl_b32 s16, s21, 6
	s_lshl_b32 s20, s90, 6
	v_lshlrev_b32_e32 v164, 1, v2
	v_add_u32_e32 v170, v11, v9
	v_add_u32_e32 v171, v12, v6
	v_add_u32_e32 v172, v13, v8
	v_add_u32_e32 v173, v1, v8
	s_branch .LBB0_218

; template <int DQK, bool NA>
; __device__ __forceinline__ void attn_unit(LAS unsigned char* lds, const bf16_t* __restrict__ Qb, const bf16_t* __restrict__ Kb, const bf16_t* __restrict__ Vtb,
;                                           bf16_t* __restrict__ Yb  , int qb, const LAS float* rpbh, int tid) {
;     ...
;     const float inv = 1.f / O2[0];
;     bf16_t* yr = Yb + (size_t)(32 * wave + r) * D;
; #pragma unroll
;     for (int q = 0; q < 4; ++q) { u32x2 o;
;         o.x = pg8::cvt_pk_bf16(O0[4 * q] * inv, O0[4 * q + 1] * inv); o.y = pg8::cvt_pk_bf16(O0[4 * q + 2] * inv, O0[4 * q + 3] * inv); *(u32x2*)(yr + 8 * q + 4 * h) = o;
;         o.x = pg8::cvt_pk_bf16(O1[4 * q] * inv, O1[4 * q + 1] * inv); o.y = pg8::cvt_pk_bf16(O1[4 * q + 2] * inv, O1[4 * q + 3] * inv); *(u32x2*)(yr + 32 + 8 * q + 4 * h) = o; }
; __global__ void __launch_bounds__(NTHR) fwd_megakernel(Args a_unused) {
;     ...
;                 if (pm & 2) for (int u = vb; u < 528; u += G) {
;                     int b, hh, qb; if (u < 512) { b = u / 128; hh = (u % 128) / 32; qb = 1 + (u & 31); } else { const int v = u - 512; b = v / 4; hh = v % 4; qb = 0; }
.LBB0_261:
	v_div_scale_f32 v1, s[34:35], v18, v18, 1.0
	v_rcp_f32_e32 v2, v1
	s_ashr_i32 s97, s96, 31
	s_lshl_b64 s[2:3], s[96:97], 11
	s_add_u32 s16, s74, s2
	v_fma_f32 v3, -v1, v2, 1.0
	v_fmac_f32_e32 v2, v3, v2
	v_div_scale_f32 v3, vcc, 1.0, v18, 1.0
	v_mul_f32_e32 v4, v3, v2
	v_fma_f32 v5, -v1, v4, v3
	s_addc_u32 s18, s75, s3
	s_lshl_b32 s2, s53, 6
	v_fmac_f32_e32 v4, v5, v2
	s_ashr_i32 s3, s2, 31
	v_fma_f32 v1, -v1, v4, v3
	s_lshl_b64 s[2:3], s[2:3], 1
	v_div_fmas_f32 v1, v1, v2, v4
	s_add_u32 s2, s16, s2
	v_div_fixup_f32 v1, v1, v18, 1.0
	s_addc_u32 s3, s18, s3
	v_mul_f32_e32 v4, v1, v82
	v_mul_f32_e32 v5, v1, v83
	v_lshl_add_u64 v[2:3], s[2:3], 0, v[182:183]
	v_mov_b32_e32 v195, v0
	v_cvt_pk_f16_f32 v4, v4, v5
	v_mul_f32_e32 v5, v1, v84
	v_mul_f32_e32 v6, v1, v85
	v_lshl_add_u64 v[2:3], v[2:3], 0, v[194:195]
	v_cvt_pk_f16_f32 v5, v5, v6
	global_store_dwordx2 v[2:3], v[4:5], off offset:1536
	v_mul_f32_e32 v4, v1, v66
	v_mul_f32_e32 v5, v1, v67
	v_cvt_pk_f16_f32 v4, v4, v5
	v_mul_f32_e32 v5, v1, v68
	v_mul_f32_e32 v6, v1, v69
	v_cvt_pk_f16_f32 v5, v5, v6
	global_store_dwordx2 v[2:3], v[4:5], off offset:1600
	v_mul_f32_e32 v4, v1, v86
	v_mul_f32_e32 v5, v1, v87
	v_cvt_pk_f16_f32 v4, v4, v5
	v_mul_f32_e32 v5, v1, v88
	v_mul_f32_e32 v6, v1, v89
	v_cvt_pk_f16_f32 v5, v5, v6
	global_store_dwordx2 v[2:3], v[4:5], off offset:1552
	v_mul_f32_e32 v4, v1, v70
	v_mul_f32_e32 v5, v1, v71
	v_cvt_pk_f16_f32 v4, v4, v5
	v_mul_f32_e32 v5, v1, v72
	v_mul_f32_e32 v6, v1, v73
	v_cvt_pk_f16_f32 v5, v5, v6
	global_store_dwordx2 v[2:3], v[4:5], off offset:1616
	v_mul_f32_e32 v4, v1, v90
	v_mul_f32_e32 v5, v1, v91
	v_cvt_pk_f16_f32 v4, v4, v5
	v_mul_f32_e32 v5, v1, v92
	v_mul_f32_e32 v6, v1, v93
	v_cvt_pk_f16_f32 v5, v5, v6
	global_store_dwordx2 v[2:3], v[4:5], off offset:1568
	v_mul_f32_e32 v4, v1, v74
	v_mul_f32_e32 v5, v1, v75
	v_cvt_pk_f16_f32 v4, v4, v5
	v_mul_f32_e32 v5, v1, v76
	v_mul_f32_e32 v6, v1, v77
	v_cvt_pk_f16_f32 v5, v5, v6
	global_store_dwordx2 v[2:3], v[4:5], off offset:1632
	v_mul_f32_e32 v4, v1, v94
	v_mul_f32_e32 v5, v1, v95
	v_cvt_pk_f16_f32 v4, v4, v5
	v_mul_f32_e32 v5, v1, v96
	v_mul_f32_e32 v6, v1, v97
	v_cvt_pk_f16_f32 v5, v5, v6
	global_store_dwordx2 v[2:3], v[4:5], off offset:1584
	v_mul_f32_e32 v4, v1, v78
	v_mul_f32_e32 v5, v1, v79
	v_cvt_pk_f16_f32 v4, v4, v5
	v_mul_f32_e32 v5, v1, v80
	v_mul_f32_e32 v1, v1, v81
	s_add_i32 s93, s93, s90
	v_cvt_pk_f16_f32 v5, v5, v1
	global_store_dwordx2 v[2:3], v[4:5], off offset:1648
	s_cmpk_lg_i32 s90, 0x100
	s_cbranch_scc1 .Lna_cont
	s_cmpk_lt_i32 s93, 0x200
	s_cbranch_scc1 .Lna_cont
	s_addk_i32 s93, 0xfff0
	s_cmpk_lt_i32 s93, 0x200
	s_cbranch_scc1 .LBB0_507
.Lna_cont:
	s_cmpk_gt_i32 s93, 0x20f
	s_cbranch_scc1 .LBB0_507

; #define LAS __attribute__((address_space(3)))
; __device__ __forceinline__ void mixprep_tile(ArgP a, int l, int tl, LAS unsigned char* lds, int tid, int wave, int lane, int pm) {
;     const TileGeo g = tile_geo(tl);
; __global__ void __launch_bounds__(NTHR) fwd_megakernel(Args a_unused) {
;     ...
;                 if (pm & 4) for (int tl = bid; tl < 528; tl += G) mixprep_tile(a, l, tl, lds, tid, wave, lane, pm);
.LBB0_769:
	v_readlane_b32 s0, v254, 48
	s_mov_b32 s15, s89
	s_cmpk_lg_i32 s90, 0x100
	s_cbranch_scc1 .Ltile_noremap
	s_add_i32 s15, s15, 16
	s_and_b32 s15, s15, 0xff
.Ltile_noremap:
	s_cmpk_gt_i32 s15, 0x20f
	s_mov_b32 s21, 0x7e00000
	v_lshl_add_u32 v1, s0, 6, v14
	s_cbranch_scc1 .LBB0_776
	v_readlane_b32 s0, v254, 48
	v_lshlrev_b32_e32 v2, 5, v14
	s_lshl_b32 s12, s0, 3
	s_mul_i32 s2, s0, 0x1020
	v_and_b32_e32 v4, 32, v2
	s_movk_i32 s0, 0x204
	v_lshl_add_u32 v5, v14, 3, 0
	v_and_b32_e32 v7, -2, v1
	v_mad_u32_u24 v8, v4, s0, 0
	s_add_u32 s0, s10, 0x1f770000
	s_addc_u32 s1, s11, 0
	v_ashrrev_i32_e32 v3, 7, v1
	v_bfe_u32 v2, v1, 1, 6
	s_lshl_b32 s13, s15, 6
	s_lshl_b32 s14, s90, 6
	v_add_u32_e32 v6, s2, v5
	v_add_u32_e32 v7, v8, v7
	v_lshlrev_b32_e32 v4, 1, v4
	s_branch .LBB0_772
